# v88 plus prompt attention: lane^32 exchanges via v_permlane32_swap instead of ds_bpermute, P.V transposed LDS reads issued ahead of the MFMAs
# speedup vs baseline: 1.0004x; 1.0004x over previous
.LBB0_525:
	s_and_b64 vcc, exec, s[8:9]
	s_cbranch_vccz .LBB0_381
	s_cmpk_gt_u32 s86, 0x317
	s_mov_b64 s[8:9], -1
	s_cbranch_scc1 .LBB0_529
	s_add_u32 s62, s80, 0xee19000
	s_addc_u32 s63, s81, 0
	s_sub_i32 s8, s86, 24
	s_lshr_b32 s72, s8, 8
	s_bfe_u32 s60, s8, 0x30005
	s_lshl_b32 s8, s8, 3
	s_lshl_b32 s84, s72, 1
	s_and_b32 s8, s8, 0xf8
	v_readlane_b32 s9, v253, 15
	s_add_i32 s8, s8, s9
	s_sub_i32 s9, 8, s84
	s_lshr_b32 s75, s8, s9
	s_lshl_b32 s9, -1, s9
	s_andn2_b32 s10, s8, s9
	s_lshl_b32 s85, s10, 5
	v_ashrrev_i32_e32 v2, 4, v172
	v_add_u32_e32 v118, s85, v2
	v_lshlrev_b32_e32 v3, 3, v172
	v_lshlrev_b32_e32 v4, s84, v118
	v_and_b32_e32 v3, 0x78, v3
	v_add_u32_e32 v4, s75, v4
	v_mov_b64_e32 v[28:29], s[62:63]
	v_mad_i64_i32 v[4:5], s[8:9], v4, s83, v[28:29]
	s_lshl_b32 s70, s60, 8
	v_lshlrev_b32_e32 v82, 1, v3
	v_add_lshl_u32 v3, v118, 4, s84
	v_lshl_add_u64 v[4:5], v[4:5], 0, s[70:71]
	v_add_u32_e32 v3, s75, v3
	v_lshl_add_u64 v[4:5], v[4:5], 0, v[82:83]
	v_mad_i64_i32 v[6:7], s[8:9], v3, s83, v[28:29]
	v_add_lshl_u32 v3, v118, 8, s84
	v_add_co_u32_e32 v4, vcc, s82, v4
	v_lshl_add_u64 v[6:7], v[6:7], 0, s[70:71]
	v_add_u32_e32 v3, s75, v3
	v_addc_co_u32_e32 v5, vcc, 0, v5, vcc
	v_lshl_add_u64 v[6:7], v[6:7], 0, v[82:83]
	v_mad_i64_i32 v[12:13], s[8:9], v3, s83, v[28:29]
	v_add_lshl_u32 v3, v118, 12, s84
	v_add_co_u32_e32 v8, vcc, s82, v6
	v_lshl_add_u64 v[12:13], v[12:13], 0, s[70:71]
	v_add_u32_e32 v3, s75, v3
	v_addc_co_u32_e32 v9, vcc, 0, v7, vcc
	v_lshl_add_u64 v[12:13], v[12:13], 0, v[82:83]
	v_mad_i64_i32 v[14:15], s[8:9], v3, s83, v[28:29]
	v_add_lshl_u32 v3, v118, 16, s84
	v_add_co_u32_e32 v12, vcc, s82, v12
	v_lshl_add_u64 v[14:15], v[14:15], 0, s[70:71]
	v_add_u32_e32 v3, s75, v3
	v_addc_co_u32_e32 v13, vcc, 0, v13, vcc
	v_lshl_add_u64 v[14:15], v[14:15], 0, v[82:83]
	v_mad_i64_i32 v[20:21], s[8:9], v3, s83, v[28:29]
	v_add_lshl_u32 v3, v118, 20, s84
	v_add_co_u32_e32 v16, vcc, s82, v14
	v_lshl_add_u64 v[20:21], v[20:21], 0, s[70:71]
	v_add_u32_e32 v3, s75, v3
	v_addc_co_u32_e32 v17, vcc, 0, v15, vcc
	v_lshl_add_u64 v[20:21], v[20:21], 0, v[82:83]
	v_mad_i64_i32 v[22:23], s[8:9], v3, s83, v[28:29]
	v_add_lshl_u32 v3, v118, 24, s84
	v_add_co_u32_e32 v20, vcc, s82, v20
	v_lshl_add_u64 v[22:23], v[22:23], 0, s[70:71]
	v_add_u32_e32 v3, s75, v3
	v_addc_co_u32_e32 v21, vcc, 0, v21, vcc
	v_lshl_add_u64 v[22:23], v[22:23], 0, v[82:83]
	v_mad_i64_i32 v[30:31], s[8:9], v3, s83, v[28:29]
	v_add_lshl_u32 v3, v118, 28, s84
	v_add_co_u32_e32 v24, vcc, s82, v22
	v_lshl_add_u64 v[30:31], v[30:31], 0, s[70:71]
	v_add_u32_e32 v3, s75, v3
	v_addc_co_u32_e32 v25, vcc, 0, v23, vcc
	v_lshl_add_u64 v[30:31], v[30:31], 0, v[82:83]
	v_mad_i64_i32 v[28:29], s[8:9], v3, s83, v[28:29]
	v_add_co_u32_e32 v30, vcc, s82, v30
	v_lshl_add_u64 v[28:29], v[28:29], 0, s[70:71]
	s_nop 0
	v_addc_co_u32_e32 v31, vcc, 0, v31, vcc
	v_lshl_add_u64 v[28:29], v[28:29], 0, v[82:83]
	v_add_co_u32_e32 v32, vcc, s82, v28
	global_load_dwordx4 v[4:7], v[4:5], off offset:2048
	s_nop 0
	global_load_dwordx4 v[8:11], v[8:9], off offset:2048
	v_addc_co_u32_e32 v33, vcc, 0, v29, vcc
	global_load_dwordx4 v[12:15], v[12:13], off offset:2048
	s_nop 0
	global_load_dwordx4 v[16:19], v[16:17], off offset:2048
	s_nop 0
	global_load_dwordx4 v[20:23], v[20:21], off offset:2048
	s_nop 0
	global_load_dwordx4 v[24:27], v[24:25], off offset:2048
	s_nop 0
	global_load_dwordx4 v[28:31], v[30:31], off offset:2048
	s_nop 0
	global_load_dwordx4 v[32:35], v[32:33], off offset:2048
	v_lshlrev_b32_e32 v3, 4, v172
	v_and_b32_e32 v3, 0xf0, v3
	v_add_u32_e32 v3, s94, v3
	v_mul_lo_u32 v36, v2, s5
	v_and_b32_e32 v120, 31, v172
	v_add_u32_e32 v121, v3, v36
	v_ashrrev_i32_e32 v119, 5, v172
	v_mov_b32_e32 v3, s94
	s_waitcnt vmcnt(0)
	ds_write_b128 v121, v[4:7]
	ds_write_b128 v121, v[8:11] offset:1088
	ds_write_b128 v121, v[12:15] offset:2176
	ds_write_b128 v121, v[16:19] offset:3264
	ds_write_b128 v121, v[20:23] offset:4352
	ds_write_b128 v121, v[24:27] offset:5440
	ds_write_b128 v121, v[28:31] offset:6528
	ds_write_b128 v121, v[32:35] offset:7616
	v_mad_u32_u24 v3, v120, s5, v3
	v_lshlrev_b32_e32 v4, 4, v119
	s_waitcnt lgkmcnt(0)
	v_add_u32_e32 v122, v3, v4
	ds_read_b128 v[84:87], v122
	ds_read_b128 v[88:91], v122 offset:32
	ds_read_b128 v[92:95], v122 offset:64
	ds_read_b128 v[96:99], v122 offset:96
	ds_read_b128 v[100:103], v122 offset:128
	ds_read_b128 v[104:107], v122 offset:160
	ds_read_b128 v[108:111], v122 offset:192
	ds_read_b128 v[112:115], v122 offset:224
	v_lshlrev_b32_e32 v67, 2, v119
	v_bfe_u32 v3, v172, 2, 2
	v_or_b32_e32 v5, v3, v67
	v_add_u32_e32 v66, 8, v67
	v_and_b32_e32 v4, 16, v172
	v_mul_lo_u32 v70, v5, s5
	v_lshlrev_b32_e32 v5, 2, v172
	s_waitcnt lgkmcnt(0)
	v_and_or_b32 v74, v5, 12, v4
	v_or_b32_e32 v4, v66, v3
	v_add_u32_e32 v69, 16, v67
	v_add_u32_e32 v68, 24, v67
	s_lshl_b32 s87, s60, 7
	v_mul_lo_u32 v71, v4, s5
	v_or_b32_e32 v4, v69, v3
	v_or_b32_e32 v3, v68, v3
	v_mul_lo_u32 v72, v4, s5
	v_mul_lo_u32 v73, v3, s5
	s_cmp_gt_u32 s10, 3
	s_mov_b64 s[8:9], -1
	s_cbranch_scc0 .LBB0_546
	s_add_i32 s8, s85, 0xffffff80
	v_add_u32_e32 v32, s8, v2
	v_lshlrev_b32_e32 v2, s84, v32
	v_add_u32_e32 v2, s75, v2
	v_mov_b64_e32 v[30:31], s[62:63]
	v_mad_i64_i32 v[2:3], s[8:9], v2, s83, v[30:31]
	s_lshl_b32 s70, s87, 1
	v_add_lshl_u32 v6, v32, 4, s84
	v_lshl_add_u64 v[2:3], v[2:3], 0, s[70:71]
	v_add_u32_e32 v6, s75, v6
	v_lshl_add_u64 v[2:3], v[2:3], 0, v[82:83]
	v_mad_i64_i32 v[6:7], s[8:9], v6, s83, v[30:31]
	v_add_lshl_u32 v10, v32, 8, s84
	v_add_co_u32_e32 v34, vcc, 0x2000, v2
	v_lshl_add_u64 v[6:7], v[6:7], 0, s[70:71]
	v_add_u32_e32 v10, s75, v10
	v_addc_co_u32_e32 v35, vcc, 0, v3, vcc
	v_lshl_add_u64 v[6:7], v[6:7], 0, v[82:83]
	v_mad_i64_i32 v[10:11], s[8:9], v10, s83, v[30:31]
	v_add_lshl_u32 v14, v32, 12, s84
	v_add_co_u32_e32 v38, vcc, 0x2000, v6
	v_lshl_add_u64 v[10:11], v[10:11], 0, s[70:71]
	v_add_u32_e32 v14, s75, v14
	v_addc_co_u32_e32 v39, vcc, 0, v7, vcc
	v_lshl_add_u64 v[10:11], v[10:11], 0, v[82:83]
	v_mad_i64_i32 v[14:15], s[8:9], v14, s83, v[30:31]
	v_add_lshl_u32 v18, v32, 16, s84
	v_add_co_u32_e32 v42, vcc, 0x2000, v10
	v_lshl_add_u64 v[14:15], v[14:15], 0, s[70:71]
	v_add_u32_e32 v18, s75, v18
	v_addc_co_u32_e32 v43, vcc, 0, v11, vcc
	v_lshl_add_u64 v[14:15], v[14:15], 0, v[82:83]
	v_mad_i64_i32 v[18:19], s[8:9], v18, s83, v[30:31]
	v_add_lshl_u32 v22, v32, 20, s84
	v_add_co_u32_e32 v46, vcc, 0x2000, v14
	v_lshl_add_u64 v[18:19], v[18:19], 0, s[70:71]
	v_add_u32_e32 v22, s75, v22
	v_addc_co_u32_e32 v47, vcc, 0, v15, vcc
	v_lshl_add_u64 v[18:19], v[18:19], 0, v[82:83]
	v_mad_i64_i32 v[22:23], s[8:9], v22, s83, v[30:31]
	v_add_lshl_u32 v26, v32, 24, s84
	global_load_dwordx4 v[2:5], v[34:35], off
	global_load_dwordx4 v[6:9], v[38:39], off
	v_add_co_u32_e32 v50, vcc, 0x2000, v18
	v_lshl_add_u64 v[22:23], v[22:23], 0, s[70:71]
	v_add_u32_e32 v26, s75, v26
	v_addc_co_u32_e32 v51, vcc, 0, v19, vcc
	v_lshl_add_u64 v[22:23], v[22:23], 0, v[82:83]
	v_mad_i64_i32 v[26:27], s[8:9], v26, s83, v[30:31]
	v_add_lshl_u32 v32, v32, 28, s84
	global_load_dwordx4 v[10:13], v[42:43], off
	global_load_dwordx4 v[14:17], v[46:47], off
	v_add_co_u32_e32 v54, vcc, 0x2000, v22
	v_lshl_add_u64 v[26:27], v[26:27], 0, s[70:71]
	v_add_u32_e32 v32, s75, v32
	v_addc_co_u32_e32 v55, vcc, 0, v23, vcc
	v_lshl_add_u64 v[26:27], v[26:27], 0, v[82:83]
	v_mad_i64_i32 v[30:31], s[8:9], v32, s83, v[30:31]
	global_load_dwordx4 v[18:21], v[50:51], off
	global_load_dwordx4 v[22:25], v[54:55], off
	v_add_co_u32_e32 v58, vcc, 0x2000, v26
	v_lshl_add_u64 v[30:31], v[30:31], 0, s[70:71]
	s_nop 0
	v_addc_co_u32_e32 v59, vcc, 0, v27, vcc
	v_lshl_add_u64 v[30:31], v[30:31], 0, v[82:83]
	global_load_dwordx4 v[26:29], v[58:59], off
	v_add_co_u32_e32 v62, vcc, 0x2000, v30
	v_or_b32_e32 v75, 2, v67
	s_nop 0
	v_addc_co_u32_e32 v63, vcc, 0, v31, vcc
	global_load_dwordx4 v[30:33], v[62:63], off
	s_nop 0
	global_load_dwordx4 v[34:37], v[34:35], off offset:2048
	s_nop 0
	global_load_dwordx4 v[38:41], v[38:39], off offset:2048
	s_nop 0
	global_load_dwordx4 v[42:45], v[42:43], off offset:2048
	s_nop 0
	global_load_dwordx4 v[46:49], v[46:47], off offset:2048
	s_nop 0
	global_load_dwordx4 v[50:53], v[50:51], off offset:2048
	s_nop 0
	global_load_dwordx4 v[54:57], v[54:55], off offset:2048
	s_nop 0
	global_load_dwordx4 v[58:61], v[58:59], off offset:2048
	s_nop 0
	global_load_dwordx4 v[62:65], v[62:63], off offset:2048
	v_cmp_ge_i32_e32 vcc, v67, v120
	v_add_u32_e32 v80, 17, v67
	s_waitcnt vmcnt(15)
	ds_write_b128 v121, v[2:5]
	s_waitcnt vmcnt(14)
	ds_write_b128 v121, v[6:9] offset:1088
	s_waitcnt vmcnt(13)
	ds_write_b128 v121, v[10:13] offset:2176
	s_waitcnt vmcnt(12)
	ds_write_b128 v121, v[14:17] offset:3264
	s_waitcnt vmcnt(11)
	ds_write_b128 v121, v[18:21] offset:4352
	s_waitcnt vmcnt(10)
	ds_write_b128 v121, v[22:25] offset:5440
	s_waitcnt vmcnt(9)
	ds_write_b128 v121, v[26:29] offset:6528
	s_waitcnt vmcnt(8)
	ds_write_b128 v121, v[30:33] offset:7616
	s_waitcnt lgkmcnt(0)
	ds_read_b128 v[2:5], v122
	ds_read_b128 v[18:21], v122 offset:32
	ds_read_b128 v[22:25], v122 offset:64
	ds_read_b128 v[26:29], v122 offset:96
	ds_read_b128 v[30:33], v122 offset:128
	ds_read_b128 v[76:79], v122 offset:160
	ds_read_b128 v[124:127], v122 offset:192
	ds_read_b128 v[128:131], v122 offset:224
	s_waitcnt lgkmcnt(7)
	v_mfma_f32_32x32x16_bf16 v[2:17], v[2:5], v[84:87], 0
	v_add_u32_e32 v81, 18, v67
	s_mov_b32 s8, 0xff800000
	v_add_u32_e32 v139, 19, v67
	v_add_u32_e32 v140, 25, v67
	v_add_u32_e32 v141, 26, v67
	v_add_u32_e32 v142, 27, v67
	s_waitcnt vmcnt(7)
	ds_write_b128 v121, v[34:37]
	s_waitcnt vmcnt(6)
	ds_write_b128 v121, v[38:41] offset:1088
	s_waitcnt vmcnt(5)
	ds_write_b128 v121, v[42:45] offset:2176
	s_waitcnt vmcnt(4)
	ds_write_b128 v121, v[46:49] offset:3264
	s_waitcnt vmcnt(3)
	ds_write_b128 v121, v[50:53] offset:4352
	s_waitcnt vmcnt(2)
	ds_write_b128 v121, v[54:57] offset:5440
	s_waitcnt vmcnt(1)
	ds_write_b128 v121, v[58:61] offset:6528
	s_waitcnt vmcnt(0)
	ds_write_b128 v121, v[62:65] offset:7616
	s_waitcnt lgkmcnt(14)
	v_mfma_f32_32x32x16_bf16 v[2:17], v[18:21], v[88:91], v[2:17]
	v_or_b32_e32 v18, 1, v67
	v_and_b32_e32 v20, 64, v249
	v_xor_b32_e32 v19, 32, v249
	v_add_u32_e32 v20, 64, v20
	s_waitcnt lgkmcnt(0)
	v_lshl_add_u32 v138, v74, 1, s93
	v_add_u32_e32 v123, v138, v70
	s_waitcnt lgkmcnt(13)
	v_mfma_f32_32x32x16_bf16 v[2:17], v[22:25], v[92:95], v[2:17]
	v_add_u32_e32 v152, 0x80, v138
	v_add_u32_e32 v132, v152, v71
	v_add_u32_e32 v133, v152, v72
	s_waitcnt lgkmcnt(12)
	v_mfma_f32_32x32x16_bf16 v[2:17], v[26:29], v[96:99], v[2:17]
	s_waitcnt lgkmcnt(11)
	v_mfma_f32_32x32x16_bf16 v[2:17], v[30:33], v[100:103], v[2:17]
	s_waitcnt lgkmcnt(10)
	v_mfma_f32_32x32x16_bf16 v[2:17], v[76:79], v[104:107], v[2:17]
	v_or_b32_e32 v76, 3, v67
	v_add_u32_e32 v77, 9, v67
	v_add_u32_e32 v78, 10, v67
	v_add_u32_e32 v79, 11, v67
	s_waitcnt lgkmcnt(9)
	v_mfma_f32_32x32x16_bf16 v[2:17], v[124:127], v[108:111], v[2:17]
	v_add_u32_e32 v124, v138, v71
	v_add_u32_e32 v125, v138, v72
	v_add_u32_e32 v126, v138, v73
	s_waitcnt lgkmcnt(8)
	v_mfma_f32_32x32x16_bf16 v[2:17], v[128:131], v[112:115], v[2:17]
	v_add_u32_e32 v131, v152, v70
	s_nop 10
	v_cndmask_b32_e32 v2, v228, v2, vcc
	v_cmp_ge_i32_e32 vcc, v18, v120
	s_nop 1
	v_cndmask_b32_e32 v3, v228, v3, vcc
	v_cmp_ge_i32_e32 vcc, v75, v120
	v_max3_f32 v18, v2, s8, v3
	s_mov_b32 s8, 0xf149f2ca
	v_cndmask_b32_e32 v4, v228, v4, vcc
	v_cmp_ge_i32_e32 vcc, v76, v120
	s_nop 1
	v_cndmask_b32_e32 v5, v228, v5, vcc
	v_cmp_ge_i32_e32 vcc, v66, v120
	v_max3_f32 v18, v18, v4, v5
	s_nop 0
	v_cndmask_b32_e32 v6, v228, v6, vcc
	v_cmp_ge_i32_e32 vcc, v77, v120
	s_nop 1
	v_cndmask_b32_e32 v7, v228, v7, vcc
	v_cmp_ge_i32_e32 vcc, v78, v120
	v_max3_f32 v18, v18, v6, v7
	s_nop 0
	v_cndmask_b32_e32 v8, v228, v8, vcc
	v_cmp_ge_i32_e32 vcc, v79, v120
	s_nop 1
	v_cndmask_b32_e32 v9, v228, v9, vcc
	v_cmp_ge_i32_e32 vcc, v69, v120
	v_max3_f32 v18, v18, v8, v9
	s_nop 0
	v_cndmask_b32_e32 v10, v228, v10, vcc
	v_cmp_ge_i32_e32 vcc, v80, v120
	s_nop 1
	v_cndmask_b32_e32 v11, v228, v11, vcc
	v_cmp_ge_i32_e32 vcc, v81, v120
	v_max3_f32 v18, v18, v10, v11
	s_nop 0
	v_cndmask_b32_e32 v12, v228, v12, vcc
	v_cmp_ge_i32_e32 vcc, v139, v120
	s_nop 1
	v_cndmask_b32_e32 v13, v228, v13, vcc
	v_cmp_ge_i32_e32 vcc, v68, v120
	v_max3_f32 v18, v18, v12, v13
	s_nop 0
	v_cndmask_b32_e32 v14, v228, v14, vcc
	v_cmp_ge_i32_e32 vcc, v140, v120
	s_nop 1
	v_cndmask_b32_e32 v15, v228, v15, vcc
	v_cmp_ge_i32_e32 vcc, v141, v120
	v_max3_f32 v18, v18, v14, v15
	s_nop 0
	v_cndmask_b32_e32 v16, v228, v16, vcc
	v_cmp_ge_i32_e32 vcc, v142, v120
	s_nop 1
	v_cndmask_b32_e32 v17, v228, v17, vcc
	v_cmp_lt_i32_e32 vcc, v19, v20
	v_max3_f32 v18, v18, v16, v17
	s_nop 0
	v_cndmask_b32_e32 v19, v249, v19, vcc
	v_lshlrev_b32_e32 v19, 2, v19
	v_mov_b32_e32 v20, v18
	v_mov_b32_e32 v190, v18
	s_nop 1
	v_permlane32_swap_b32_e32 v20, v190
	s_nop 1
	v_max3_f32 v116, v20, v190, s8
	v_sub_f32_e32 v2, v2, v116
	v_exp_f32_e32 v20, v2
	v_sub_f32_e32 v3, v3, v116
	v_exp_f32_e32 v21, v3
	v_sub_f32_e32 v3, v4, v116
	v_exp_f32_e32 v22, v3
	v_sub_f32_e32 v3, v5, v116
	v_exp_f32_e32 v23, v3
	v_sub_f32_e32 v3, v6, v116
	v_add_f32_e32 v2, 0, v20
	v_exp_f32_e32 v24, v3
	v_sub_f32_e32 v3, v7, v116
	v_add_f32_e32 v2, v21, v2
	v_exp_f32_e32 v25, v3
	v_sub_f32_e32 v3, v8, v116
	v_add_f32_e32 v2, v22, v2
	v_exp_f32_e32 v26, v3
	v_sub_f32_e32 v3, v9, v116
	v_add_f32_e32 v2, v23, v2
	v_exp_f32_e32 v27, v3
	v_sub_f32_e32 v3, v10, v116
	v_add_f32_e32 v2, v24, v2
	v_exp_f32_e32 v28, v3
	v_sub_f32_e32 v3, v11, v116
	v_add_f32_e32 v2, v25, v2
	v_exp_f32_e32 v29, v3
	v_sub_f32_e32 v3, v12, v116
	v_add_f32_e32 v2, v26, v2
	v_exp_f32_e32 v30, v3
	v_sub_f32_e32 v3, v13, v116
	v_add_f32_e32 v2, v27, v2
	v_exp_f32_e32 v31, v3
	v_sub_f32_e32 v3, v14, v116
	v_add_f32_e32 v2, v28, v2
	v_exp_f32_e32 v32, v3
	v_sub_f32_e32 v3, v15, v116
	v_add_f32_e32 v2, v29, v2
	v_exp_f32_e32 v33, v3
	v_sub_f32_e32 v3, v16, v116
	v_add_f32_e32 v2, v30, v2
	v_exp_f32_e32 v34, v3
	v_sub_f32_e32 v3, v17, v116
	v_add_f32_e32 v2, v31, v2
	v_exp_f32_e32 v35, v3
	v_add_f32_e32 v2, v32, v2
	v_add_f32_e32 v2, v33, v2
	v_add_f32_e32 v2, v34, v2
	v_sub_f32_e32 v18, 0xf149f2ca, v116
	v_add_f32_e32 v36, v35, v2
	v_exp_f32_e32 v143, v18
	v_mov_b32_e32 v18, v36
	v_mov_b32_e32 v190, v36
	s_nop 1
	v_permlane32_swap_b32_e32 v18, v190
	s_nop 0
	v_bfe_u32 v19, v25, 16, 1
	s_nop 0
	v_bfe_u32 v37, v26, 16, 1
	v_add_f32_e32 v117, v18, v190
	v_bfe_u32 v18, v27, 16, 1
	v_add3_u32 v18, v27, v18, s73
	v_bfe_u32 v36, v24, 16, 1
	v_add3_u32 v19, v25, v19, s73
	v_add3_u32 v26, v26, v37, s73
	v_add3_u32 v24, v24, v36, s73
	v_lshrrev_b32_e32 v24, 16, v24
	v_lshrrev_b32_e32 v25, 16, v26
	v_and_or_b32 v147, v18, s33, v25
	v_and_or_b32 v146, v19, s33, v24
	v_cvt_pk_bf16_f32 v145, v22, v23
	v_mul_f32_e32 v2, 0, v143
	v_cvt_pk_bf16_f32 v144, v20, v21
	v_mov_b32_e32 v3, v2
	v_mov_b32_e32 v4, v2
	v_mov_b32_e32 v5, v2
	v_mov_b32_e32 v6, v2
	v_mov_b32_e32 v7, v2
	v_mov_b32_e32 v8, v2
	v_mov_b32_e32 v9, v2
	v_mov_b32_e32 v10, v2
	v_mov_b32_e32 v11, v2
	v_mov_b32_e32 v12, v2
	v_mov_b32_e32 v13, v2
	v_mov_b32_e32 v14, v2
	v_mov_b32_e32 v15, v2
	v_mov_b32_e32 v16, v2
	v_mov_b32_e32 v17, v2
	v_cvt_pk_bf16_f32 v151, v34, v35
	v_cvt_pk_bf16_f32 v150, v32, v33
	v_cvt_pk_bf16_f32 v149, v30, v31
	v_cvt_pk_bf16_f32 v148, v28, v29
	ds_read_b64_tr_b16 v[18:19], v123
	ds_read_b64_tr_b16 v[20:21], v124
	s_waitcnt lgkmcnt(0)
	v_add_u32_e32 v22, 64, v138
	v_mfma_f32_32x32x16_bf16 v[50:65], v[18:21], v[144:147], v[2:17]
	ds_read_b64_tr_b16 v[18:19], v125
	ds_read_b64_tr_b16 v[20:21], v126
	s_waitcnt lgkmcnt(0)
	v_add_u32_e32 v127, v22, v70
	v_add_u32_e32 v128, v22, v71
	v_add_u32_e32 v129, v22, v72
	v_add_u32_e32 v130, v22, v73
	v_add_u32_e32 v138, 0xc0, v138
	v_fmac_f32_e32 v117, 0, v143
	v_mfma_f32_32x32x16_bf16 v[50:65], v[18:21], v[148:151], v[50:65]
	ds_read_b64_tr_b16 v[18:19], v127
	ds_read_b64_tr_b16 v[20:21], v128
	s_waitcnt lgkmcnt(0)
	s_nop 0
	v_mfma_f32_32x32x16_bf16 v[34:49], v[18:21], v[144:147], v[2:17]
	ds_read_b64_tr_b16 v[18:19], v129
	ds_read_b64_tr_b16 v[20:21], v130
	s_waitcnt lgkmcnt(0)
	ds_read_b64_tr_b16 v[134:135], v131
	ds_read_b64_tr_b16 v[136:137], v132
	s_waitcnt lgkmcnt(0)
	s_nop 0
	v_mfma_f32_32x32x16_bf16 v[34:49], v[18:21], v[148:151], v[34:49]
	v_mfma_f32_32x32x16_bf16 v[18:33], v[134:137], v[144:147], v[2:17]
	v_add_u32_e32 v134, v152, v73
	ds_read_b64_tr_b16 v[152:153], v133
	ds_read_b64_tr_b16 v[154:155], v134
	s_waitcnt lgkmcnt(0)
	v_add_u32_e32 v135, v138, v70
	v_add_u32_e32 v136, v138, v71
	v_add_u32_e32 v137, v138, v72
	v_add_u32_e32 v138, v138, v73
	v_mfma_f32_32x32x16_bf16 v[18:33], v[152:155], v[148:151], v[18:33]
	ds_read_b64_tr_b16 v[152:153], v135
	ds_read_b64_tr_b16 v[154:155], v136
	s_waitcnt lgkmcnt(0)
	s_nop 0
	v_mfma_f32_32x32x16_bf16 v[2:17], v[152:155], v[144:147], v[2:17]
	ds_read_b64_tr_b16 v[144:145], v137
	ds_read_b64_tr_b16 v[146:147], v138
	s_waitcnt lgkmcnt(0)
	s_nop 0
	v_mfma_f32_32x32x16_bf16 v[2:17], v[144:147], v[148:151], v[2:17]
	s_cbranch_execz .LBB0_547
	s_branch .LBB0_548

.LBB0_549:
	v_add_u32_e32 v139, s88, v118
	v_add_u32_e32 v66, 0xffffffa0, v139
	v_lshlrev_b32_e32 v66, s84, v66
	v_add_u32_e32 v66, s75, v66
	v_mov_b64_e32 v[152:153], s[62:63]
	v_add_u32_e32 v70, 0xffffffa4, v139
	v_mad_i64_i32 v[66:67], s[64:65], v66, s83, v[152:153]
	s_lshl_b32 s70, s87, 1
	v_lshlrev_b32_e32 v70, s84, v70
	v_lshl_add_u64 v[66:67], v[66:67], 0, s[70:71]
	v_add_u32_e32 v70, s75, v70
	v_add_u32_e32 v74, 0xffffffa8, v139
	v_lshl_add_u64 v[66:67], v[66:67], 0, v[82:83]
	v_mad_i64_i32 v[70:71], s[64:65], v70, s83, v[152:153]
	v_lshlrev_b32_e32 v74, s84, v74
	v_add_co_u32_e32 v156, vcc, 0x2000, v66
	v_lshl_add_u64 v[70:71], v[70:71], 0, s[70:71]
	v_add_u32_e32 v74, s75, v74
	v_add_u32_e32 v78, 0xffffffac, v139
	v_addc_co_u32_e32 v157, vcc, 0, v67, vcc
	v_lshl_add_u64 v[70:71], v[70:71], 0, v[82:83]
	v_mad_i64_i32 v[74:75], s[64:65], v74, s83, v[152:153]
	v_lshlrev_b32_e32 v78, s84, v78
	v_add_co_u32_e32 v160, vcc, 0x2000, v70
	v_lshl_add_u64 v[74:75], v[74:75], 0, s[70:71]
	v_add_u32_e32 v78, s75, v78
	v_add_u32_e32 v140, 0xffffffb0, v139
	v_addc_co_u32_e32 v161, vcc, 0, v71, vcc
	v_lshl_add_u64 v[74:75], v[74:75], 0, v[82:83]
	v_mad_i64_i32 v[78:79], s[64:65], v78, s83, v[152:153]
	v_lshlrev_b32_e32 v140, s84, v140
	v_add_co_u32_e32 v164, vcc, 0x2000, v74
	v_lshl_add_u64 v[78:79], v[78:79], 0, s[70:71]
	v_add_u32_e32 v140, s75, v140
	v_add_u32_e32 v144, 0xffffffb4, v139
	v_addc_co_u32_e32 v165, vcc, 0, v75, vcc
	v_lshl_add_u64 v[78:79], v[78:79], 0, v[82:83]
	v_mad_i64_i32 v[140:141], s[64:65], v140, s83, v[152:153]
	v_lshlrev_b32_e32 v144, s84, v144
	v_add_co_u32_e32 v168, vcc, 0x2000, v78
	v_lshl_add_u64 v[140:141], v[140:141], 0, s[70:71]
	v_add_u32_e32 v144, s75, v144
	v_add_u32_e32 v148, 0xffffffb8, v139
	v_addc_co_u32_e32 v169, vcc, 0, v79, vcc
	v_lshl_add_u64 v[140:141], v[140:141], 0, v[82:83]
	v_mad_i64_i32 v[144:145], s[64:65], v144, s83, v[152:153]
	v_lshlrev_b32_e32 v148, s84, v148
	global_load_dwordx4 v[66:69], v[156:157], off
	global_load_dwordx4 v[70:73], v[160:161], off
	v_add_co_u32_e32 v174, vcc, 0x2000, v140
	v_lshl_add_u64 v[144:145], v[144:145], 0, s[70:71]
	v_add_u32_e32 v148, s75, v148
	v_add_u32_e32 v139, 0xffffffbc, v139
	v_addc_co_u32_e32 v175, vcc, 0, v141, vcc
	v_lshl_add_u64 v[144:145], v[144:145], 0, v[82:83]
	v_mad_i64_i32 v[148:149], s[64:65], v148, s83, v[152:153]
	v_lshlrev_b32_e32 v139, s84, v139
	global_load_dwordx4 v[74:77], v[164:165], off
	global_load_dwordx4 v[78:81], v[168:169], off
	v_add_co_u32_e32 v178, vcc, 0x2000, v144
	v_lshl_add_u64 v[148:149], v[148:149], 0, s[70:71]
	v_add_u32_e32 v139, s75, v139
	v_addc_co_u32_e32 v179, vcc, 0, v145, vcc
	v_lshl_add_u64 v[148:149], v[148:149], 0, v[82:83]
	v_mad_i64_i32 v[152:153], s[64:65], v139, s83, v[152:153]
	global_load_dwordx4 v[140:143], v[174:175], off
	global_load_dwordx4 v[144:147], v[178:179], off
	v_add_co_u32_e32 v182, vcc, 0x2000, v148
	v_lshl_add_u64 v[152:153], v[152:153], 0, s[70:71]
	s_nop 0
	v_addc_co_u32_e32 v183, vcc, 0, v149, vcc
	v_lshl_add_u64 v[152:153], v[152:153], 0, v[82:83]
	global_load_dwordx4 v[148:151], v[182:183], off
	v_add_co_u32_e32 v186, vcc, 0x2000, v152
	s_cmpk_lg_i32 s88, 0x60
	s_nop 0
	v_addc_co_u32_e32 v187, vcc, 0, v153, vcc
	global_load_dwordx4 v[152:155], v[186:187], off
	s_nop 0
	global_load_dwordx4 v[156:159], v[156:157], off offset:2048
	s_nop 0
	global_load_dwordx4 v[160:163], v[160:161], off offset:2048
	s_nop 0
	global_load_dwordx4 v[164:167], v[164:165], off offset:2048
	s_nop 0
	global_load_dwordx4 v[168:171], v[168:169], off offset:2048
	s_nop 0
	global_load_dwordx4 v[174:177], v[174:175], off offset:2048
	s_nop 0
	global_load_dwordx4 v[178:181], v[178:179], off offset:2048
	s_nop 0
	global_load_dwordx4 v[182:185], v[182:183], off offset:2048
	s_nop 0
	global_load_dwordx4 v[186:189], v[186:187], off offset:2048
	s_waitcnt vmcnt(15)
	ds_write_b128 v121, v[66:69]
	s_waitcnt vmcnt(14)
	ds_write_b128 v121, v[70:73] offset:1088
	s_waitcnt vmcnt(13)
	ds_write_b128 v121, v[74:77] offset:2176
	s_waitcnt vmcnt(12)
	ds_write_b128 v121, v[78:81] offset:3264
	s_waitcnt vmcnt(11)
	ds_write_b128 v121, v[140:143] offset:4352
	s_waitcnt vmcnt(10)
	ds_write_b128 v121, v[144:147] offset:5440
	s_waitcnt vmcnt(9)
	ds_write_b128 v121, v[148:151] offset:6528
	s_waitcnt vmcnt(8)
	ds_write_b128 v121, v[152:155] offset:7616
	s_waitcnt lgkmcnt(0)
	ds_read_b128 v[66:69], v122
	ds_read_b128 v[140:143], v122 offset:32
	s_waitcnt lgkmcnt(1)
	v_mfma_f32_32x32x16_bf16 v[66:81], v[66:69], v[84:87], 0
	s_cselect_b64 s[64:65], -1, 0
	s_or_b64 vcc, s[8:9], s[64:65]
	s_mov_b32 s70, 0xff800000
	s_waitcnt lgkmcnt(0)
	v_mfma_f32_32x32x16_bf16 v[66:81], v[140:143], v[88:91], v[66:81]
	ds_read_b128 v[140:143], v122 offset:64
	ds_read_b128 v[144:147], v122 offset:96
	s_waitcnt lgkmcnt(1)
	v_mfma_f32_32x32x16_bf16 v[66:81], v[140:143], v[92:95], v[66:81]
	s_waitcnt lgkmcnt(0)
	v_mfma_f32_32x32x16_bf16 v[66:81], v[144:147], v[96:99], v[66:81]
	ds_read_b128 v[140:143], v122 offset:128
	ds_read_b128 v[144:147], v122 offset:160
	s_waitcnt lgkmcnt(1)
	v_mfma_f32_32x32x16_bf16 v[66:81], v[140:143], v[100:103], v[66:81]
	s_waitcnt lgkmcnt(0)
	v_mfma_f32_32x32x16_bf16 v[66:81], v[144:147], v[104:107], v[66:81]
	ds_read_b128 v[140:143], v122 offset:192
	ds_read_b128 v[144:147], v122 offset:224
	s_waitcnt vmcnt(7)
	ds_write_b128 v121, v[156:159]
	s_waitcnt vmcnt(6)
	ds_write_b128 v121, v[160:163] offset:1088
	s_waitcnt vmcnt(5)
	ds_write_b128 v121, v[164:167] offset:2176
	s_waitcnt vmcnt(4)
	ds_write_b128 v121, v[168:171] offset:3264
	s_waitcnt vmcnt(3)
	ds_write_b128 v121, v[174:177] offset:4352
	s_waitcnt vmcnt(2)
	ds_write_b128 v121, v[178:181] offset:5440
	s_waitcnt vmcnt(1)
	ds_write_b128 v121, v[182:185] offset:6528
	s_waitcnt vmcnt(0)
	ds_write_b128 v121, v[186:189] offset:7616
	s_waitcnt lgkmcnt(0)
	s_waitcnt lgkmcnt(9)
	v_mfma_f32_32x32x16_bf16 v[66:81], v[140:143], v[108:111], v[66:81]
	v_and_b32_e32 v141, 64, v249
	v_xor_b32_e32 v140, 32, v249
	v_add_u32_e32 v141, 64, v141
	s_waitcnt lgkmcnt(8)
	v_mfma_f32_32x32x16_bf16 v[66:81], v[144:147], v[112:115], v[66:81]
	s_nop 11
	v_cndmask_b32_e32 v139, v228, v66, vcc
	s_or_b64 vcc, s[10:11], s[64:65]
	v_cndmask_b32_e32 v67, v228, v67, vcc
	s_or_b64 vcc, s[12:13], s[64:65]
	v_cndmask_b32_e32 v68, v228, v68, vcc
	s_or_b64 vcc, s[14:15], s[64:65]
	v_cndmask_b32_e32 v69, v228, v69, vcc
	s_or_b64 vcc, s[16:17], s[64:65]
	v_cndmask_b32_e32 v70, v228, v70, vcc
	s_or_b64 vcc, s[18:19], s[64:65]
	v_cndmask_b32_e32 v71, v228, v71, vcc
	s_or_b64 vcc, s[20:21], s[64:65]
	v_cndmask_b32_e32 v72, v228, v72, vcc
	s_or_b64 vcc, s[22:23], s[64:65]
	v_cndmask_b32_e32 v73, v228, v73, vcc
	s_or_b64 vcc, s[24:25], s[64:65]
	v_cndmask_b32_e32 v74, v228, v74, vcc
	s_or_b64 vcc, s[26:27], s[64:65]
	v_cndmask_b32_e32 v75, v228, v75, vcc
	s_or_b64 vcc, s[28:29], s[64:65]
	v_cndmask_b32_e32 v76, v228, v76, vcc
	s_or_b64 vcc, s[30:31], s[64:65]
	v_max3_f32 v66, v139, s70, v67
	v_cndmask_b32_e32 v77, v228, v77, vcc
	s_or_b64 vcc, s[34:35], s[64:65]
	v_max3_f32 v66, v66, v68, v69
	v_cndmask_b32_e32 v78, v228, v78, vcc
	s_or_b64 vcc, s[36:37], s[64:65]
	v_max3_f32 v66, v66, v70, v71
	v_cndmask_b32_e32 v79, v228, v79, vcc
	v_max3_f32 v66, v66, v72, v73
	s_or_b64 vcc, s[38:39], s[64:65]
	v_max3_f32 v66, v66, v74, v75
	v_cndmask_b32_e32 v80, v228, v80, vcc
	s_or_b64 vcc, s[40:41], s[64:65]
	v_max3_f32 v66, v66, v76, v77
	v_cndmask_b32_e32 v81, v228, v81, vcc
	v_cmp_lt_i32_e32 vcc, v140, v141
	v_max3_f32 v66, v66, v78, v79
	v_max3_f32 v66, v66, v80, v81
	v_cndmask_b32_e32 v140, v249, v140, vcc
	v_lshlrev_b32_e32 v140, 2, v140
	v_mov_b32_e32 v141, v66
	v_mov_b32_e32 v190, v66
	s_nop 1
	v_permlane32_swap_b32_e32 v141, v190
	s_nop 1
	v_max3_f32 v66, v116, v141, v190
	v_sub_f32_e32 v139, v139, v66
	v_exp_f32_e32 v139, v139
	v_sub_f32_e32 v67, v67, v66
	v_exp_f32_e32 v67, v67
	v_sub_f32_e32 v68, v68, v66
	v_exp_f32_e32 v142, v68
	v_sub_f32_e32 v68, v69, v66
	v_exp_f32_e32 v69, v68
	v_sub_f32_e32 v68, v70, v66
	v_add_f32_e32 v141, 0, v139
	v_exp_f32_e32 v70, v68
	v_sub_f32_e32 v71, v71, v66
	v_add_f32_e32 v68, v67, v141
	v_exp_f32_e32 v71, v71
	v_sub_f32_e32 v72, v72, v66
	v_add_f32_e32 v68, v142, v68
	v_exp_f32_e32 v72, v72
	v_sub_f32_e32 v73, v73, v66
	v_add_f32_e32 v68, v69, v68
	v_exp_f32_e32 v73, v73
	v_sub_f32_e32 v74, v74, v66
	v_add_f32_e32 v68, v70, v68
	v_exp_f32_e32 v74, v74
	v_sub_f32_e32 v75, v75, v66
	v_add_f32_e32 v68, v71, v68
	v_exp_f32_e32 v75, v75
	v_sub_f32_e32 v76, v76, v66
	v_add_f32_e32 v68, v72, v68
	v_exp_f32_e32 v76, v76
	v_sub_f32_e32 v77, v77, v66
	v_add_f32_e32 v68, v73, v68
	v_exp_f32_e32 v77, v77
	v_sub_f32_e32 v78, v78, v66
	v_add_f32_e32 v68, v74, v68
	v_exp_f32_e32 v78, v78
	v_add_f32_e32 v68, v75, v68
	v_add_f32_e32 v68, v76, v68
	v_add_f32_e32 v68, v77, v68
	v_add_f32_e32 v141, v78, v68
	v_sub_f32_e32 v68, v79, v66
	v_exp_f32_e32 v79, v68
	v_sub_f32_e32 v68, v80, v66
	v_sub_f32_e32 v116, v116, v66
	v_exp_f32_e32 v80, v68
	v_sub_f32_e32 v68, v81, v66
	v_exp_f32_e32 v81, v68
	v_exp_f32_e32 v68, v116
	v_add_f32_e32 v116, v79, v141
	v_bfe_u32 v141, v73, 16, 1
	v_bfe_u32 v143, v71, 16, 1
	v_bfe_u32 v144, v69, 16, 1
	v_pk_mul_f32 v[64:65], v[64:65], v[68:69] op_sel_hi:[1,0]
	v_pk_mul_f32 v[62:63], v[62:63], v[68:69] op_sel_hi:[1,0]
	v_pk_mul_f32 v[60:61], v[60:61], v[68:69] op_sel_hi:[1,0]
	v_pk_mul_f32 v[58:59], v[58:59], v[68:69] op_sel_hi:[1,0]
	v_pk_mul_f32 v[56:57], v[56:57], v[68:69] op_sel_hi:[1,0]
	v_pk_mul_f32 v[54:55], v[54:55], v[68:69] op_sel_hi:[1,0]
	v_pk_mul_f32 v[52:53], v[52:53], v[68:69] op_sel_hi:[1,0]
	v_pk_mul_f32 v[50:51], v[50:51], v[68:69] op_sel_hi:[1,0]
	v_pk_mul_f32 v[48:49], v[48:49], v[68:69] op_sel_hi:[1,0]
	v_pk_mul_f32 v[46:47], v[46:47], v[68:69] op_sel_hi:[1,0]
	v_pk_mul_f32 v[44:45], v[44:45], v[68:69] op_sel_hi:[1,0]
	v_pk_mul_f32 v[42:43], v[42:43], v[68:69] op_sel_hi:[1,0]
	v_pk_mul_f32 v[40:41], v[40:41], v[68:69] op_sel_hi:[1,0]
	v_pk_mul_f32 v[38:39], v[38:39], v[68:69] op_sel_hi:[1,0]
	v_pk_mul_f32 v[36:37], v[36:37], v[68:69] op_sel_hi:[1,0]
	v_pk_mul_f32 v[34:35], v[34:35], v[68:69] op_sel_hi:[1,0]
	v_pk_mul_f32 v[32:33], v[32:33], v[68:69] op_sel_hi:[1,0]
	v_add3_u32 v69, v69, v144, s73
	v_add3_u32 v71, v71, v143, s73
	v_add3_u32 v73, v73, v141, s73
	v_bfe_u32 v143, v142, 16, 1
	v_bfe_u32 v144, v70, 16, 1
	v_bfe_u32 v145, v72, 16, 1
	v_add3_u32 v72, v72, v145, s73
	v_add3_u32 v70, v70, v144, s73
	v_add3_u32 v142, v142, v143, s73
	v_lshrrev_b32_e32 v141, 16, v142
	v_lshrrev_b32_e32 v70, 16, v70
	v_lshrrev_b32_e32 v72, 16, v72
	v_add_f32_e32 v116, v80, v116
	v_and_or_b32 v73, v73, s33, v72
	v_and_or_b32 v72, v71, s33, v70
	v_and_or_b32 v71, v69, s33, v141
	v_cvt_pk_bf16_f32 v70, v139, v67
	v_bfe_u32 v67, v81, 16, 1
	v_bfe_u32 v69, v79, 16, 1
	v_bfe_u32 v139, v77, 16, 1
	v_bfe_u32 v141, v75, 16, 1
	v_add_f32_e32 v116, v81, v116
	v_add3_u32 v141, v75, v141, s73
	v_add3_u32 v75, v77, v139, s73
	v_add3_u32 v69, v79, v69, s73
	v_add3_u32 v67, v81, v67, s73
	v_bfe_u32 v79, v76, 16, 1
	v_bfe_u32 v81, v78, 16, 1
	v_bfe_u32 v139, v80, 16, 1
	v_bfe_u32 v77, v74, 16, 1
	v_add3_u32 v80, v80, v139, s73
	v_add3_u32 v78, v78, v81, s73
	v_add3_u32 v76, v76, v79, s73
	v_add3_u32 v74, v74, v77, s73
	v_lshrrev_b32_e32 v139, 16, v76
	v_lshrrev_b32_e32 v76, 16, v78
	v_lshrrev_b32_e32 v77, 16, v80
	ds_read_b64_tr_b16 v[192:193], v123
	ds_read_b64_tr_b16 v[194:195], v124
	ds_read_b64_tr_b16 v[196:197], v125
	ds_read_b64_tr_b16 v[198:199], v126
	ds_read_b64_tr_b16 v[200:201], v127
	ds_read_b64_tr_b16 v[202:203], v128
	ds_read_b64_tr_b16 v[204:205], v129
	ds_read_b64_tr_b16 v[206:207], v130
	ds_read_b64_tr_b16 v[208:209], v131
	ds_read_b64_tr_b16 v[210:211], v132
	ds_read_b64_tr_b16 v[212:213], v133
	ds_read_b64_tr_b16 v[214:215], v134
	ds_read_b64_tr_b16 v[216:217], v135
	ds_read_b64_tr_b16 v[218:219], v136
	s_waitcnt lgkmcnt(12)
	v_lshrrev_b32_e32 v74, 16, v74
	v_mfma_f32_32x32x16_bf16 v[50:65], v[192:195], v[70:73], v[50:65]
	v_and_or_b32 v77, v67, s33, v77
	v_and_or_b32 v76, v69, s33, v76
	v_and_or_b32 v75, v75, s33, v139
	v_and_or_b32 v74, v141, s33, v74
	ds_read_b64_tr_b16 v[220:221], v137
	ds_read_b64_tr_b16 v[222:223], v138
	s_waitcnt lgkmcnt(12)
	v_mul_f32_e64 v30, v30, v68
	v_mul_f32_e64 v31, v31, v68
	v_pk_mul_f32 v[28:29], v[28:29], v[68:69] op_sel_hi:[1,0]
	v_mfma_f32_32x32x16_bf16 v[50:65], v[196:199], v[74:77], v[50:65]
	s_waitcnt lgkmcnt(10)
	v_mul_f32_e64 v26, v26, v68
	v_mul_f32_e64 v27, v27, v68
	v_mul_f32_e64 v24, v24, v68
	v_mul_f32_e64 v25, v25, v68
	v_mul_f32_e64 v22, v22, v68
	v_mul_f32_e64 v23, v23, v68
	v_pk_mul_f32 v[20:21], v[20:21], v[68:69] op_sel_hi:[1,0]
	v_pk_mul_f32 v[18:19], v[18:19], v[68:69] op_sel_hi:[1,0]
	v_pk_mul_f32 v[16:17], v[16:17], v[68:69] op_sel_hi:[1,0]
	v_mfma_f32_32x32x16_bf16 v[34:49], v[200:203], v[70:73], v[34:49]
	s_waitcnt lgkmcnt(8)
	v_mul_f32_e64 v14, v14, v68
	v_mul_f32_e64 v15, v15, v68
	v_mul_f32_e64 v12, v12, v68
	v_mul_f32_e64 v13, v13, v68
	v_mul_f32_e64 v10, v10, v68
	v_mul_f32_e64 v11, v11, v68
	v_pk_mul_f32 v[8:9], v[8:9], v[68:69] op_sel_hi:[1,0]
	v_pk_mul_f32 v[6:7], v[6:7], v[68:69] op_sel_hi:[1,0]
	v_pk_mul_f32 v[4:5], v[4:5], v[68:69] op_sel_hi:[1,0]
	v_mfma_f32_32x32x16_bf16 v[34:49], v[204:207], v[74:77], v[34:49]
	s_waitcnt lgkmcnt(6)
	v_mul_f32_e64 v2, v2, v68
	v_mul_f32_e64 v3, v3, v68
	v_mov_b32_e32 v67, v116
	v_mov_b32_e32 v190, v116
	s_nop 1
	v_permlane32_swap_b32_e32 v67, v190
	s_nop 1
	v_add_f32_e32 v67, v67, v190
	v_mfma_f32_32x32x16_bf16 v[18:33], v[208:211], v[70:73], v[18:33]
	s_waitcnt lgkmcnt(4)
	v_fmac_f32_e32 v67, v117, v68
	v_mov_b32_e32 v116, v66
	v_mov_b32_e32 v117, v67
	v_mfma_f32_32x32x16_bf16 v[18:33], v[212:215], v[74:77], v[18:33]
	s_waitcnt lgkmcnt(2)
	s_nop 0
	v_mfma_f32_32x32x16_bf16 v[2:17], v[216:219], v[70:73], v[2:17]
	s_waitcnt lgkmcnt(0)
	s_nop 0
	v_mfma_f32_32x32x16_bf16 v[2:17], v[220:223], v[74:77], v[2:17]
	s_add_i32 s88, s88, 32
	s_cmpk_eq_i32 s88, 0x80
	s_cbranch_scc1 .LBB0_552
